# workgroups that finish the up / w_in GEMM one tile early issue an early L2 write-back while they wait (on top of v23)
# baseline (speedup 1.0000x reference)
.LBB0_265:
	s_cmpk_lt_u32 s80, 82
	s_cbranch_scc1 .Lwb_skip_win
	v_readfirstlane_b32 s0, v198
	s_cmpk_lt_u32 s0, 64
	s_cbranch_scc0 .Lwb_skip_win
	buffer_wbl2 sc1

.LBB0_1177:
	s_cmpk_lt_u32 s80, 172
	s_cbranch_scc1 .Lwb_skip_up
	v_readfirstlane_b32 s0, v198
	s_cmpk_lt_u32 s0, 64
	s_cbranch_scc0 .Lwb_skip_up
	buffer_wbl2 sc1
